# v65 + first-iteration vmcnt relax kept only in the peeled K-iteration (loop proper back to a plain wait, no per-iteration compare/branch)
# baseline (speedup 1.0000x reference)
; #define PG8_STAGE(bufoff, gbase, voff) do { _Pragma("unroll") for (int _i = 0; _i < 2; ++_i) \
;         __builtin_amdgcn_global_load_lds((const unsigned*)((const char*)(gbase) + (voff)[_i]), (LAS unsigned*)(lds + (bufoff) + ldsw + _i * 8192), 16, 0, 0); } while (0)
; #define PG8_LDA(dst, b, h) do { _Pragma("unroll") for (int m = 0; m < 4; ++m) _Pragma("unroll") for (int k = 0; k < 2; ++k) dst[m][k] = *(const LAS bf16x8*)(lds + PG8_SA(b, h) + aoff + m * 2048 + k * 1024); } while (0)
; #define PG8_LDB(dst, b, h) do { _Pragma("unroll") for (int n = 0; n < 2; ++n) _Pragma("unroll") for (int k = 0; k < 2; ++k) dst[n][k] = *(const LAS bf16x8*)(lds + PG8_SB(b, h) + boff + n * 2048 + k * 1024); } while (0)
; #define PG8_MMA(ai, bj, At, Bt) do { __builtin_amdgcn_s_setprio(1); _Pragma("unroll") for (int m = 0; m < 4; ++m) _Pragma("unroll") for (int n = 0; n < 2; ++n) _Pragma("unroll") for (int k = 0; k < 2; ++k) \
;         acc[ai][bj][m][n] = __builtin_amdgcn_mfma_f32_16x16x32_bf16(Bt[n][k], At[m][k], acc[ai][bj][m][n], 0, 0, 0); __builtin_amdgcn_s_setprio(0); } while (0)
; #define PG8_WAIT_V(n) asm volatile("s_waitcnt vmcnt(" #n ")" ::: "memory")
; #define PG8_WAIT_L(n) asm volatile("s_waitcnt lgkmcnt(" #n ")" ::: "memory")
; #define PG8_BAR __builtin_amdgcn_s_barrier()
; #define PG8_SCHED __builtin_amdgcn_sched_barrier(0)
; template <class Epi, bool ALIGN_EPI = PG8_ALIGN, bool SP2 = PG8_SP2>
; __device__ __forceinline__ void gemm_phase(LAS uchar* lds, const Gemm g, const StaticOrder& S, const Epi& E) {
;     ...
;         for (int t = tb; t < tb + tblk; t += 2) {
;             const bool last = (t == nt - 2);
;             const char* a1 = cA + (size_t)(t + 1) * kstep;
;             const char* a2 = last ? nA : cA + (size_t)(t + 2) * kstep; const char* b2 = last ? nB : cB + (size_t)(t + 2) * kstep;
;             const char* a3 = a2 + kstep; const char* b3 = b2 + kstep;
;             if constexpr (SP2) {
;             PG8_LDB(B0, 0, 0); PG8_LDB(B1, 0, 1); PG8_SCHED; PG8_LDA(At, 0, 0); PG8_STAGE(PG8_SA(1, 1), a1 + hstepA, voffA);
;             PG8_WAIT_V(8); PG8_WAIT_L(0); PG8_BAR; PG8_MMA(0, 0, At, B0); PG8_MMA(0, 1, At, B1); PG8_BAR; PG8_SCHED;
.LBB0_344:
	s_add_u32 s38, s4, 0x100
	s_addc_u32 s39, s5, 0
	s_mov_b32 s40, -2
	s_add_u32 s18, s16, 0x100
	s_addc_u32 s19, s17, 0
	s_add_i32 s41, 0, 0x10000
	s_cmp_eq_u32 s40, 12
	s_cselect_b32 s21, s7, s19
	s_cselect_b32 s20, s6, s18
	v_add_u32_e32 v168, s41, v139
	s_cselect_b32 s5, s15, s39
	s_cselect_b32 s4, s14, s38
	s_add_i32 s42, 0, 0x14000
	ds_read_b128 v[164:167], v168
	ds_read_b128 v[172:175], v168 offset:1024
	ds_read_b128 v[176:179], v168 offset:2048
	ds_read_b128 v[184:187], v168 offset:3072
	v_add_u32_e32 v168, s42, v139
	ds_read_b128 v[188:191], v168
	ds_read_b128 v[192:195], v168 offset:1024
	ds_read_b128 v[196:199], v168 offset:2048
	ds_read_b128 v[200:203], v168 offset:3072
	v_lshl_add_u64 v[168:169], s[16:17], 0, v[160:161]
	s_add_i32 m0, s25, 0xc000
	ds_read_b128 v[204:207], v171
	ds_read_b128 v[208:211], v171 offset:1024
	ds_read_b128 v[212:215], v171 offset:2048
	ds_read_b128 v[216:219], v171 offset:3072
	ds_read_b128 v[220:223], v171 offset:4096
	ds_read_b128 v[224:227], v171 offset:5120
	ds_read_b128 v[228:231], v171 offset:6144
	ds_read_b128 v[232:235], v171 offset:7168
	global_load_lds_dwordx4 v[168:169], off
	v_lshl_add_u64 v[168:169], s[16:17], 0, v[162:163]
	s_add_i32 m0, s25, 0xe000
	s_nop 0
	global_load_lds_dwordx4 v[168:169], off
	s_cmp_eq_u32 s97, 1
	s_cbranch_scc0 .Lrw_std_345_0_pl
	s_waitcnt vmcnt(24)
	s_branch .Lrw_done_345_0_pl

; #define PG8_STAGE(bufoff, gbase, voff) do { _Pragma("unroll") for (int _i = 0; _i < 2; ++_i) \
;         __builtin_amdgcn_global_load_lds((const unsigned*)((const char*)(gbase) + (voff)[_i]), (LAS unsigned*)(lds + (bufoff) + ldsw + _i * 8192), 16, 0, 0); } while (0)
; #define PG8_LDA(dst, b, h) do { _Pragma("unroll") for (int m = 0; m < 4; ++m) _Pragma("unroll") for (int k = 0; k < 2; ++k) dst[m][k] = *(const LAS bf16x8*)(lds + PG8_SA(b, h) + aoff + m * 2048 + k * 1024); } while (0)
; #define PG8_MMA(ai, bj, At, Bt) do { __builtin_amdgcn_s_setprio(1); _Pragma("unroll") for (int m = 0; m < 4; ++m) _Pragma("unroll") for (int n = 0; n < 2; ++n) _Pragma("unroll") for (int k = 0; k < 2; ++k) \
;         acc[ai][bj][m][n] = __builtin_amdgcn_mfma_f32_16x16x32_bf16(Bt[n][k], At[m][k], acc[ai][bj][m][n], 0, 0, 0); __builtin_amdgcn_s_setprio(0); } while (0)
; #define PG8_WAIT_V(n) asm volatile("s_waitcnt vmcnt(" #n ")" ::: "memory")
; #define PG8_WAIT_L(n) asm volatile("s_waitcnt lgkmcnt(" #n ")" ::: "memory")
; #define PG8_BAR __builtin_amdgcn_s_barrier()
; #define PG8_SCHED __builtin_amdgcn_sched_barrier(0)
; template <class Epi, bool ALIGN_EPI = PG8_ALIGN, bool SP2 = PG8_SP2>
; __device__ __forceinline__ void gemm_phase(LAS uchar* lds, const Gemm g, const StaticOrder& S, const Epi& E) {
;     ...
;             PG8_WAIT_V(8); PG8_WAIT_L(0); PG8_BAR; PG8_MMA(0, 0, At, B0); PG8_MMA(0, 1, At, B1); PG8_BAR; PG8_SCHED;
;             PG8_LDA(At, 0, 1); PG8_STAGE(PG8_SB(0, 0), b2, voffB); PG8_STAGE(PG8_SB(0, 1), b2 + hstepB, voffB); PG8_STAGE(PG8_SA(0, 0), a2, voffA);
;             PG8_WAIT_V(8); PG8_WAIT_L(0); PG8_BAR; PG8_MMA(1, 0, At, B0); PG8_MMA(1, 1, At, B1); PG8_BAR; PG8_SCHED;
.Lrw_done_345_0_pl:
	s_waitcnt lgkmcnt(0)
	s_barrier
	s_setprio 1
	s_waitcnt lgkmcnt(0)
	v_mfma_f32_16x16x32_bf16 v[126:129], v[164:167], v[204:207], 0
	v_mfma_f32_16x16x32_bf16 v[122:125], v[176:179], v[204:207], 0
	v_mfma_f32_16x16x32_bf16 v[118:121], v[164:167], v[212:215], 0
	v_mfma_f32_16x16x32_bf16 v[110:113], v[176:179], v[212:215], 0
	v_mfma_f32_16x16x32_bf16 v[102:105], v[164:167], v[220:223], 0
	v_mfma_f32_16x16x32_bf16 v[94:97], v[176:179], v[220:223], 0
	v_mfma_f32_16x16x32_bf16 v[86:89], v[164:167], v[228:231], 0
	v_mfma_f32_16x16x32_bf16 v[78:81], v[176:179], v[228:231], 0
	v_mfma_f32_16x16x32_bf16 v[126:129], v[172:175], v[208:211], v[126:129]
	v_mfma_f32_16x16x32_bf16 v[122:125], v[184:187], v[208:211], v[122:125]
	v_mfma_f32_16x16x32_bf16 v[118:121], v[172:175], v[216:219], v[118:121]
	v_mfma_f32_16x16x32_bf16 v[110:113], v[184:187], v[216:219], v[110:113]
	v_mfma_f32_16x16x32_bf16 v[102:105], v[172:175], v[224:227], v[102:105]
	v_mfma_f32_16x16x32_bf16 v[94:97], v[184:187], v[224:227], v[94:97]
	v_mfma_f32_16x16x32_bf16 v[86:89], v[172:175], v[232:235], v[86:89]
	v_mfma_f32_16x16x32_bf16 v[78:81], v[184:187], v[232:235], v[78:81]
	s_setprio 0
	s_setprio 1
	v_mfma_f32_16x16x32_bf16 v[114:117], v[188:191], v[204:207], 0
	v_mfma_f32_16x16x32_bf16 v[106:109], v[196:199], v[204:207], 0
	v_mfma_f32_16x16x32_bf16 v[98:101], v[188:191], v[212:215], 0
	v_mfma_f32_16x16x32_bf16 v[90:93], v[196:199], v[212:215], 0
	v_mfma_f32_16x16x32_bf16 v[82:85], v[188:191], v[220:223], 0
	v_mfma_f32_16x16x32_bf16 v[74:77], v[196:199], v[220:223], 0
	v_mfma_f32_16x16x32_bf16 v[70:73], v[188:191], v[228:231], 0
	v_mfma_f32_16x16x32_bf16 v[66:69], v[196:199], v[228:231], 0
	v_mfma_f32_16x16x32_bf16 v[114:117], v[192:195], v[208:211], v[114:117]
	v_mfma_f32_16x16x32_bf16 v[106:109], v[200:203], v[208:211], v[106:109]
	v_mfma_f32_16x16x32_bf16 v[98:101], v[192:195], v[216:219], v[98:101]
	v_mfma_f32_16x16x32_bf16 v[90:93], v[200:203], v[216:219], v[90:93]
	v_mfma_f32_16x16x32_bf16 v[82:85], v[192:195], v[224:227], v[82:85]
	v_mfma_f32_16x16x32_bf16 v[74:77], v[200:203], v[224:227], v[74:77]
	v_mfma_f32_16x16x32_bf16 v[70:73], v[192:195], v[232:235], v[70:73]
	v_mfma_f32_16x16x32_bf16 v[66:69], v[200:203], v[232:235], v[66:69]
	s_setprio 0
	s_barrier
	s_add_i32 s16, s41, s23
	v_lshl_add_u64 v[168:169], s[4:5], 0, v[134:135]
	s_mov_b32 m0, s16
	ds_read_b128 v[204:207], v171 offset:16384
	ds_read_b128 v[208:211], v171 offset:17408
	ds_read_b128 v[212:215], v171 offset:18432
	ds_read_b128 v[216:219], v171 offset:19456
	ds_read_b128 v[220:223], v171 offset:20480
	ds_read_b128 v[224:227], v171 offset:21504
	ds_read_b128 v[228:231], v171 offset:22528
	ds_read_b128 v[232:235], v171 offset:23552
	global_load_lds_dwordx4 v[168:169], off
	s_add_i32 m0, s16, 0x2000
	s_add_u32 s16, s4, 0x44000
	v_lshl_add_u64 v[180:181], s[4:5], 0, v[130:131]
	s_addc_u32 s17, s5, 0
	s_add_i32 s41, s42, s23
	global_load_lds_dwordx4 v[180:181], off
	v_lshl_add_u64 v[236:237], s[16:17], 0, v[134:135]
	s_mov_b32 m0, s41
	v_lshl_add_u64 v[238:239], s[20:21], 0, v[132:133]
	global_load_lds_dwordx4 v[236:237], off
	v_lshl_add_u64 v[236:237], s[16:17], 0, v[130:131]
	s_add_i32 m0, s41, 0x2000
	s_nop 0
	global_load_lds_dwordx4 v[236:237], off
	v_lshl_add_u64 v[236:237], s[20:21], 0, v[156:157]
	s_mov_b32 m0, s25
	s_nop 0
	global_load_lds_dwordx4 v[236:237], off
	s_mov_b32 m0, s26
	s_nop 0
	global_load_lds_dwordx4 v[238:239], off
	s_cmp_eq_u32 s97, 1
	s_cbranch_scc0 .Lrw_std_345_1_pl
	s_waitcnt vmcnt(24)
	s_branch .Lrw_done_345_1_pl

; #define PG8_STAGE(bufoff, gbase, voff) do { _Pragma("unroll") for (int _i = 0; _i < 2; ++_i) \
;         __builtin_amdgcn_global_load_lds((const unsigned*)((const char*)(gbase) + (voff)[_i]), (LAS unsigned*)(lds + (bufoff) + ldsw + _i * 8192), 16, 0, 0); } while (0)
; #define PG8_LDA(dst, b, h) do { _Pragma("unroll") for (int m = 0; m < 4; ++m) _Pragma("unroll") for (int k = 0; k < 2; ++k) dst[m][k] = *(const LAS bf16x8*)(lds + PG8_SA(b, h) + aoff + m * 2048 + k * 1024); } while (0)
; #define PG8_LDB(dst, b, h) do { _Pragma("unroll") for (int n = 0; n < 2; ++n) _Pragma("unroll") for (int k = 0; k < 2; ++k) dst[n][k] = *(const LAS bf16x8*)(lds + PG8_SB(b, h) + boff + n * 2048 + k * 1024); } while (0)
; #define PG8_MMA(ai, bj, At, Bt) do { __builtin_amdgcn_s_setprio(1); _Pragma("unroll") for (int m = 0; m < 4; ++m) _Pragma("unroll") for (int n = 0; n < 2; ++n) _Pragma("unroll") for (int k = 0; k < 2; ++k) \
;         acc[ai][bj][m][n] = __builtin_amdgcn_mfma_f32_16x16x32_bf16(Bt[n][k], At[m][k], acc[ai][bj][m][n], 0, 0, 0); __builtin_amdgcn_s_setprio(0); } while (0)
; #define PG8_WAIT_V(n) asm volatile("s_waitcnt vmcnt(" #n ")" ::: "memory")
; #define PG8_WAIT_L(n) asm volatile("s_waitcnt lgkmcnt(" #n ")" ::: "memory")
; #define PG8_BAR __builtin_amdgcn_s_barrier()
; template <class Epi, bool ALIGN_EPI = PG8_ALIGN, bool SP2 = PG8_SP2>
; __device__ __forceinline__ void gemm_phase(LAS uchar* lds, const Gemm g, const StaticOrder& S, const Epi& E) {
;     ...
;         for (int t = tb; t < tb + tblk; t += 2) {
;             const bool last = (t == nt - 2);
;             const char* a1 = cA + (size_t)(t + 1) * kstep;
;             const char* a2 = last ? nA : cA + (size_t)(t + 2) * kstep; const char* b2 = last ? nB : cB + (size_t)(t + 2) * kstep;
;             const char* a3 = a2 + kstep; const char* b3 = b2 + kstep;
;             if constexpr (SP2) {
;             PG8_LDB(B0, 0, 0); PG8_LDB(B1, 0, 1); PG8_SCHED; PG8_LDA(At, 0, 0); PG8_STAGE(PG8_SA(1, 1), a1 + hstepA, voffA);
;             PG8_WAIT_V(8); PG8_WAIT_L(0); PG8_BAR; PG8_MMA(0, 0, At, B0); PG8_MMA(0, 1, At, B1); PG8_BAR; PG8_SCHED;
;             PG8_LDA(At, 0, 1); PG8_STAGE(PG8_SB(0, 0), b2, voffB); PG8_STAGE(PG8_SB(0, 1), b2 + hstepB, voffB); PG8_STAGE(PG8_SA(0, 0), a2, voffA);
;             PG8_WAIT_V(8); PG8_WAIT_L(0); PG8_BAR; PG8_MMA(1, 0, At, B0); PG8_MMA(1, 1, At, B1); PG8_BAR; PG8_SCHED;
.LBB0_345:
	s_add_u32 s18, s16, 0x100
	s_addc_u32 s19, s17, 0
	s_add_i32 s41, 0, 0x10000
	s_cmp_eq_u32 s40, 12
	s_cselect_b32 s21, s7, s19
	s_cselect_b32 s20, s6, s18
	v_add_u32_e32 v168, s41, v139
	s_cselect_b32 s5, s15, s39
	s_cselect_b32 s4, s14, s38
	s_add_i32 s42, 0, 0x14000
	ds_read_b128 v[164:167], v168
	ds_read_b128 v[172:175], v168 offset:1024
	ds_read_b128 v[176:179], v168 offset:2048
	ds_read_b128 v[184:187], v168 offset:3072
	v_add_u32_e32 v168, s42, v139
	ds_read_b128 v[188:191], v168
	ds_read_b128 v[192:195], v168 offset:1024
	ds_read_b128 v[196:199], v168 offset:2048
	ds_read_b128 v[200:203], v168 offset:3072
	v_lshl_add_u64 v[168:169], s[16:17], 0, v[160:161]
	s_add_i32 m0, s25, 0xc000
	ds_read_b128 v[204:207], v171
	ds_read_b128 v[208:211], v171 offset:1024
	ds_read_b128 v[212:215], v171 offset:2048
	ds_read_b128 v[216:219], v171 offset:3072
	ds_read_b128 v[220:223], v171 offset:4096
	ds_read_b128 v[224:227], v171 offset:5120
	ds_read_b128 v[228:231], v171 offset:6144
	ds_read_b128 v[232:235], v171 offset:7168
	global_load_lds_dwordx4 v[168:169], off
	v_lshl_add_u64 v[168:169], s[16:17], 0, v[162:163]
	s_add_i32 m0, s25, 0xe000
	s_nop 0
	global_load_lds_dwordx4 v[168:169], off
	s_waitcnt vmcnt(8)
	s_waitcnt lgkmcnt(0)
	s_barrier
	s_setprio 1
	s_waitcnt lgkmcnt(0)
	v_mfma_f32_16x16x32_bf16 v[126:129], v[164:167], v[204:207], v[126:129]
	v_mfma_f32_16x16x32_bf16 v[122:125], v[176:179], v[204:207], v[122:125]
	v_mfma_f32_16x16x32_bf16 v[118:121], v[164:167], v[212:215], v[118:121]
	v_mfma_f32_16x16x32_bf16 v[110:113], v[176:179], v[212:215], v[110:113]
	v_mfma_f32_16x16x32_bf16 v[102:105], v[164:167], v[220:223], v[102:105]
	v_mfma_f32_16x16x32_bf16 v[94:97], v[176:179], v[220:223], v[94:97]
	v_mfma_f32_16x16x32_bf16 v[86:89], v[164:167], v[228:231], v[86:89]
	v_mfma_f32_16x16x32_bf16 v[78:81], v[176:179], v[228:231], v[78:81]
	v_mfma_f32_16x16x32_bf16 v[126:129], v[172:175], v[208:211], v[126:129]
	v_mfma_f32_16x16x32_bf16 v[122:125], v[184:187], v[208:211], v[122:125]
	v_mfma_f32_16x16x32_bf16 v[118:121], v[172:175], v[216:219], v[118:121]
	v_mfma_f32_16x16x32_bf16 v[110:113], v[184:187], v[216:219], v[110:113]
	v_mfma_f32_16x16x32_bf16 v[102:105], v[172:175], v[224:227], v[102:105]
	v_mfma_f32_16x16x32_bf16 v[94:97], v[184:187], v[224:227], v[94:97]
	v_mfma_f32_16x16x32_bf16 v[86:89], v[172:175], v[232:235], v[86:89]
	v_mfma_f32_16x16x32_bf16 v[78:81], v[184:187], v[232:235], v[78:81]
	s_setprio 0
	s_setprio 1
	v_mfma_f32_16x16x32_bf16 v[114:117], v[188:191], v[204:207], v[114:117]
	v_mfma_f32_16x16x32_bf16 v[106:109], v[196:199], v[204:207], v[106:109]
	v_mfma_f32_16x16x32_bf16 v[98:101], v[188:191], v[212:215], v[98:101]
	v_mfma_f32_16x16x32_bf16 v[90:93], v[196:199], v[212:215], v[90:93]
	v_mfma_f32_16x16x32_bf16 v[82:85], v[188:191], v[220:223], v[82:85]
	v_mfma_f32_16x16x32_bf16 v[74:77], v[196:199], v[220:223], v[74:77]
	v_mfma_f32_16x16x32_bf16 v[70:73], v[188:191], v[228:231], v[70:73]
	v_mfma_f32_16x16x32_bf16 v[66:69], v[196:199], v[228:231], v[66:69]
	v_mfma_f32_16x16x32_bf16 v[114:117], v[192:195], v[208:211], v[114:117]
	v_mfma_f32_16x16x32_bf16 v[106:109], v[200:203], v[208:211], v[106:109]
	v_mfma_f32_16x16x32_bf16 v[98:101], v[192:195], v[216:219], v[98:101]
	v_mfma_f32_16x16x32_bf16 v[90:93], v[200:203], v[216:219], v[90:93]
	v_mfma_f32_16x16x32_bf16 v[82:85], v[192:195], v[224:227], v[82:85]
	v_mfma_f32_16x16x32_bf16 v[74:77], v[200:203], v[224:227], v[74:77]
	v_mfma_f32_16x16x32_bf16 v[70:73], v[192:195], v[232:235], v[70:73]
	v_mfma_f32_16x16x32_bf16 v[66:69], v[200:203], v[232:235], v[66:69]
	s_setprio 0
	s_barrier
	s_add_i32 s16, s41, s23
	v_lshl_add_u64 v[168:169], s[4:5], 0, v[134:135]
	s_mov_b32 m0, s16
	ds_read_b128 v[204:207], v171 offset:16384
	ds_read_b128 v[208:211], v171 offset:17408
	ds_read_b128 v[212:215], v171 offset:18432
	ds_read_b128 v[216:219], v171 offset:19456
	ds_read_b128 v[220:223], v171 offset:20480
	ds_read_b128 v[224:227], v171 offset:21504
	ds_read_b128 v[228:231], v171 offset:22528
	ds_read_b128 v[232:235], v171 offset:23552
	global_load_lds_dwordx4 v[168:169], off
	s_add_i32 m0, s16, 0x2000
	s_add_u32 s16, s4, 0x44000
	v_lshl_add_u64 v[180:181], s[4:5], 0, v[130:131]
	s_addc_u32 s17, s5, 0
	s_add_i32 s41, s42, s23
	global_load_lds_dwordx4 v[180:181], off
	v_lshl_add_u64 v[236:237], s[16:17], 0, v[134:135]
	s_mov_b32 m0, s41
	v_lshl_add_u64 v[238:239], s[20:21], 0, v[132:133]
	global_load_lds_dwordx4 v[236:237], off
	v_lshl_add_u64 v[236:237], s[16:17], 0, v[130:131]
	s_add_i32 m0, s41, 0x2000
	s_nop 0
	global_load_lds_dwordx4 v[236:237], off
	v_lshl_add_u64 v[236:237], s[20:21], 0, v[156:157]
	s_mov_b32 m0, s25
	s_nop 0
	global_load_lds_dwordx4 v[236:237], off
	s_mov_b32 m0, s26
	s_nop 0
	global_load_lds_dwordx4 v[238:239], off
	s_waitcnt vmcnt(8)
	s_waitcnt lgkmcnt(0)
	s_barrier
; #define PG8_STAGE(bufoff, gbase, voff) do { _Pragma("unroll") for (int _i = 0; _i < 2; ++_i) \
;         __builtin_amdgcn_global_load_lds((const unsigned*)((const char*)(gbase) + (voff)[_i]), (LAS unsigned*)(lds + (bufoff) + ldsw + _i * 8192), 16, 0, 0); } while (0)
; #define PG8_LDA(dst, b, h) do { _Pragma("unroll") for (int m = 0; m < 4; ++m) _Pragma("unroll") for (int k = 0; k < 2; ++k) dst[m][k] = *(const LAS bf16x8*)(lds + PG8_SA(b, h) + aoff + m * 2048 + k * 1024); } while (0)
; #define PG8_LDB(dst, b, h) do { _Pragma("unroll") for (int n = 0; n < 2; ++n) _Pragma("unroll") for (int k = 0; k < 2; ++k) dst[n][k] = *(const LAS bf16x8*)(lds + PG8_SB(b, h) + boff + n * 2048 + k * 1024); } while (0)
; #define PG8_MMA(ai, bj, At, Bt) do { __builtin_amdgcn_s_setprio(1); _Pragma("unroll") for (int m = 0; m < 4; ++m) _Pragma("unroll") for (int n = 0; n < 2; ++n) _Pragma("unroll") for (int k = 0; k < 2; ++k) \
;         acc[ai][bj][m][n] = __builtin_amdgcn_mfma_f32_16x16x32_bf16(Bt[n][k], At[m][k], acc[ai][bj][m][n], 0, 0, 0); __builtin_amdgcn_s_setprio(0); } while (0)
; #define PG8_WAIT_V(n) asm volatile("s_waitcnt vmcnt(" #n ")" ::: "memory")
; #define PG8_WAIT_L(n) asm volatile("s_waitcnt lgkmcnt(" #n ")" ::: "memory")
; #define PG8_BAR __builtin_amdgcn_s_barrier()
; #define PG8_SCHED __builtin_amdgcn_sched_barrier(0)
; template <class Epi, bool ALIGN_EPI = PG8_ALIGN, bool SP2 = PG8_SP2>
; __device__ __forceinline__ void gemm_phase(LAS uchar* lds, const Gemm g, const StaticOrder& S, const Epi& E) {
;     ...
;             PG8_WAIT_V(8); PG8_WAIT_L(0); PG8_BAR; PG8_MMA(1, 0, At, B0); PG8_MMA(1, 1, At, B1); PG8_BAR; PG8_SCHED;
;             PG8_LDB(B0, 1, 0); PG8_LDB(B1, 1, 1); PG8_SCHED; PG8_LDA(At, 1, 0); PG8_STAGE(PG8_SA(0, 1), a2 + hstepA, voffA);
;             PG8_WAIT_V(8); PG8_WAIT_L(0); PG8_BAR; PG8_MMA(0, 0, At, B0); PG8_MMA(0, 1, At, B1); PG8_BAR; PG8_SCHED;
	s_setprio 1
	s_waitcnt lgkmcnt(0)
	v_mfma_f32_16x16x32_bf16 v[62:65], v[164:167], v[204:207], v[62:65]
	v_mfma_f32_16x16x32_bf16 v[58:61], v[176:179], v[204:207], v[58:61]
	v_mfma_f32_16x16x32_bf16 v[54:57], v[164:167], v[212:215], v[54:57]
	v_mfma_f32_16x16x32_bf16 v[46:49], v[176:179], v[212:215], v[46:49]
	v_mfma_f32_16x16x32_bf16 v[38:41], v[164:167], v[220:223], v[38:41]
	v_mfma_f32_16x16x32_bf16 v[30:33], v[176:179], v[220:223], v[30:33]
	v_mfma_f32_16x16x32_bf16 v[22:25], v[164:167], v[228:231], v[22:25]
	v_mfma_f32_16x16x32_bf16 v[14:17], v[176:179], v[228:231], v[14:17]
	v_mfma_f32_16x16x32_bf16 v[62:65], v[172:175], v[208:211], v[62:65]
	v_mfma_f32_16x16x32_bf16 v[58:61], v[184:187], v[208:211], v[58:61]
	v_mfma_f32_16x16x32_bf16 v[54:57], v[172:175], v[216:219], v[54:57]
	v_mfma_f32_16x16x32_bf16 v[46:49], v[184:187], v[216:219], v[46:49]
	v_mfma_f32_16x16x32_bf16 v[38:41], v[172:175], v[224:227], v[38:41]
	v_mfma_f32_16x16x32_bf16 v[30:33], v[184:187], v[224:227], v[30:33]
	v_mfma_f32_16x16x32_bf16 v[22:25], v[172:175], v[232:235], v[22:25]
	v_mfma_f32_16x16x32_bf16 v[14:17], v[184:187], v[232:235], v[14:17]
	s_setprio 0
	s_setprio 1
	v_mfma_f32_16x16x32_bf16 v[50:53], v[188:191], v[204:207], v[50:53]
	v_mfma_f32_16x16x32_bf16 v[42:45], v[196:199], v[204:207], v[42:45]
	v_mfma_f32_16x16x32_bf16 v[34:37], v[188:191], v[212:215], v[34:37]
	v_mfma_f32_16x16x32_bf16 v[26:29], v[196:199], v[212:215], v[26:29]
	v_mfma_f32_16x16x32_bf16 v[18:21], v[188:191], v[220:223], v[18:21]
	v_mfma_f32_16x16x32_bf16 v[10:13], v[196:199], v[220:223], v[10:13]
	v_mfma_f32_16x16x32_bf16 v[6:9], v[188:191], v[228:231], v[6:9]
	v_mfma_f32_16x16x32_bf16 v[2:5], v[196:199], v[228:231], v[2:5]
	v_mfma_f32_16x16x32_bf16 v[50:53], v[192:195], v[208:211], v[50:53]
	v_mfma_f32_16x16x32_bf16 v[42:45], v[200:203], v[208:211], v[42:45]
	v_mfma_f32_16x16x32_bf16 v[34:37], v[192:195], v[216:219], v[34:37]
	v_mfma_f32_16x16x32_bf16 v[26:29], v[200:203], v[216:219], v[26:29]
	v_mfma_f32_16x16x32_bf16 v[18:21], v[192:195], v[224:227], v[18:21]
	v_mfma_f32_16x16x32_bf16 v[10:13], v[200:203], v[224:227], v[10:13]
	v_mfma_f32_16x16x32_bf16 v[6:9], v[192:195], v[232:235], v[6:9]
	v_mfma_f32_16x16x32_bf16 v[2:5], v[200:203], v[232:235], v[2:5]
	s_setprio 0
	s_barrier
	s_add_i32 s41, 0, 0x18000
	s_add_i32 s42, 0, 0x1c000
	v_add_u32_e32 v184, s41, v139
	v_add_u32_e32 v200, s42, v139
	ds_read_b128 v[164:167], v184
	ds_read_b128 v[172:175], v184 offset:1024
	ds_read_b128 v[176:179], v184 offset:2048
	ds_read_b128 v[184:187], v184 offset:3072
	ds_read_b128 v[188:191], v200
	ds_read_b128 v[192:195], v200 offset:1024
	ds_read_b128 v[196:199], v200 offset:2048
	ds_read_b128 v[200:203], v200 offset:3072
	s_add_u32 s16, s20, 0x44000
	s_addc_u32 s17, s21, 0
	s_mov_b32 m0, s27
	v_lshl_add_u64 v[240:241], s[16:17], 0, v[156:157]
	ds_read_b128 v[204:207], v171 offset:32768
	ds_read_b128 v[208:211], v171 offset:33792
	ds_read_b128 v[212:215], v171 offset:34816
	ds_read_b128 v[216:219], v171 offset:35840
	ds_read_b128 v[220:223], v171 offset:36864
	ds_read_b128 v[224:227], v171 offset:37888
	ds_read_b128 v[228:231], v171 offset:38912
	ds_read_b128 v[232:235], v171 offset:39936
	global_load_lds_dwordx4 v[240:241], off
	v_lshl_add_u64 v[240:241], s[16:17], 0, v[132:133]
	s_mov_b32 m0, s28
	s_nop 0
	global_load_lds_dwordx4 v[240:241], off
	s_waitcnt vmcnt(8)
	s_waitcnt lgkmcnt(0)
	s_barrier
	s_setprio 1
	s_waitcnt lgkmcnt(0)
	v_mfma_f32_16x16x32_bf16 v[126:129], v[164:167], v[204:207], v[126:129]
	v_mfma_f32_16x16x32_bf16 v[122:125], v[176:179], v[204:207], v[122:125]
	v_mfma_f32_16x16x32_bf16 v[118:121], v[164:167], v[212:215], v[118:121]
	v_mfma_f32_16x16x32_bf16 v[110:113], v[176:179], v[212:215], v[110:113]
	v_mfma_f32_16x16x32_bf16 v[102:105], v[164:167], v[220:223], v[102:105]
	v_mfma_f32_16x16x32_bf16 v[94:97], v[176:179], v[220:223], v[94:97]
	v_mfma_f32_16x16x32_bf16 v[86:89], v[164:167], v[228:231], v[86:89]
	v_mfma_f32_16x16x32_bf16 v[78:81], v[176:179], v[228:231], v[78:81]
	v_mfma_f32_16x16x32_bf16 v[126:129], v[172:175], v[208:211], v[126:129]
	v_mfma_f32_16x16x32_bf16 v[122:125], v[184:187], v[208:211], v[122:125]
	v_mfma_f32_16x16x32_bf16 v[118:121], v[172:175], v[216:219], v[118:121]
	v_mfma_f32_16x16x32_bf16 v[110:113], v[184:187], v[216:219], v[110:113]
	v_mfma_f32_16x16x32_bf16 v[102:105], v[172:175], v[224:227], v[102:105]
	v_mfma_f32_16x16x32_bf16 v[94:97], v[184:187], v[224:227], v[94:97]
	v_mfma_f32_16x16x32_bf16 v[86:89], v[172:175], v[232:235], v[86:89]
	v_mfma_f32_16x16x32_bf16 v[78:81], v[184:187], v[232:235], v[78:81]
	s_setprio 0
	s_setprio 1
	v_mfma_f32_16x16x32_bf16 v[114:117], v[188:191], v[204:207], v[114:117]
	v_mfma_f32_16x16x32_bf16 v[106:109], v[196:199], v[204:207], v[106:109]
	v_mfma_f32_16x16x32_bf16 v[98:101], v[188:191], v[212:215], v[98:101]
	v_mfma_f32_16x16x32_bf16 v[90:93], v[196:199], v[212:215], v[90:93]
	v_mfma_f32_16x16x32_bf16 v[82:85], v[188:191], v[220:223], v[82:85]
	v_mfma_f32_16x16x32_bf16 v[74:77], v[196:199], v[220:223], v[74:77]
	v_mfma_f32_16x16x32_bf16 v[70:73], v[188:191], v[228:231], v[70:73]
	v_mfma_f32_16x16x32_bf16 v[66:69], v[196:199], v[228:231], v[66:69]
	v_mfma_f32_16x16x32_bf16 v[114:117], v[192:195], v[208:211], v[114:117]
	v_mfma_f32_16x16x32_bf16 v[106:109], v[200:203], v[208:211], v[106:109]
	v_mfma_f32_16x16x32_bf16 v[98:101], v[192:195], v[216:219], v[98:101]
	v_mfma_f32_16x16x32_bf16 v[90:93], v[200:203], v[216:219], v[90:93]
	v_mfma_f32_16x16x32_bf16 v[82:85], v[192:195], v[224:227], v[82:85]
	v_mfma_f32_16x16x32_bf16 v[74:77], v[200:203], v[224:227], v[74:77]
	v_mfma_f32_16x16x32_bf16 v[70:73], v[192:195], v[232:235], v[70:73]
	v_mfma_f32_16x16x32_bf16 v[66:69], v[200:203], v[232:235], v[66:69]
	s_setprio 0
	s_barrier
; #define PG8_STAGE(bufoff, gbase, voff) do { _Pragma("unroll") for (int _i = 0; _i < 2; ++_i) \
;         __builtin_amdgcn_global_load_lds((const unsigned*)((const char*)(gbase) + (voff)[_i]), (LAS unsigned*)(lds + (bufoff) + ldsw + _i * 8192), 16, 0, 0); } while (0)
; #define PG8_LDA(dst, b, h) do { _Pragma("unroll") for (int m = 0; m < 4; ++m) _Pragma("unroll") for (int k = 0; k < 2; ++k) dst[m][k] = *(const LAS bf16x8*)(lds + PG8_SA(b, h) + aoff + m * 2048 + k * 1024); } while (0)
; #define PG8_MMA(ai, bj, At, Bt) do { __builtin_amdgcn_s_setprio(1); _Pragma("unroll") for (int m = 0; m < 4; ++m) _Pragma("unroll") for (int n = 0; n < 2; ++n) _Pragma("unroll") for (int k = 0; k < 2; ++k) \
;         acc[ai][bj][m][n] = __builtin_amdgcn_mfma_f32_16x16x32_bf16(Bt[n][k], At[m][k], acc[ai][bj][m][n], 0, 0, 0); __builtin_amdgcn_s_setprio(0); } while (0)
; #define PG8_WAIT_V(n) asm volatile("s_waitcnt vmcnt(" #n ")" ::: "memory")
; #define PG8_WAIT_L(n) asm volatile("s_waitcnt lgkmcnt(" #n ")" ::: "memory")
; #define PG8_BAR __builtin_amdgcn_s_barrier()
; #define PG8_SCHED __builtin_amdgcn_sched_barrier(0)
; template <class Epi, bool ALIGN_EPI = PG8_ALIGN, bool SP2 = PG8_SP2>
; __device__ __forceinline__ void gemm_phase(LAS uchar* lds, const Gemm g, const StaticOrder& S, const Epi& E) {
;     ...
;             PG8_WAIT_V(8); PG8_WAIT_L(0); PG8_BAR; PG8_MMA(0, 0, At, B0); PG8_MMA(0, 1, At, B1); PG8_BAR; PG8_SCHED;
;             PG8_LDA(At, 1, 1); PG8_STAGE(PG8_SB(1, 0), b3, voffB); PG8_STAGE(PG8_SB(1, 1), b3 + hstepB, voffB); PG8_STAGE(PG8_SA(1, 0), a3, voffA);
;             PG8_WAIT_V(8); PG8_WAIT_L(0); PG8_BAR; PG8_MMA(1, 0, At, B0); PG8_MMA(1, 1, At, B1); PG8_BAR; PG8_SCHED;
	s_add_i32 s16, s41, s23
	v_lshl_add_u64 v[168:169], v[168:169], 0, s[84:85]
	s_mov_b32 m0, s16
	ds_read_b128 v[204:207], v171 offset:49152
	ds_read_b128 v[208:211], v171 offset:50176
	ds_read_b128 v[212:215], v171 offset:51200
	ds_read_b128 v[216:219], v171 offset:52224
	ds_read_b128 v[220:223], v171 offset:53248
	ds_read_b128 v[224:227], v171 offset:54272
	ds_read_b128 v[228:231], v171 offset:55296
	ds_read_b128 v[232:235], v171 offset:56320
	global_load_lds_dwordx4 v[168:169], off
	s_add_i32 m0, s16, 0x2000
	s_add_u32 s4, s4, 0x44080
	v_lshl_add_u64 v[168:169], v[180:181], 0, s[84:85]
	s_addc_u32 s5, s5, 0
	s_add_i32 s16, s42, s23
	global_load_lds_dwordx4 v[168:169], off
	v_lshl_add_u64 v[168:169], s[4:5], 0, v[134:135]
	s_mov_b32 m0, s16
	s_nop 0
	global_load_lds_dwordx4 v[168:169], off
	v_lshl_add_u64 v[168:169], s[4:5], 0, v[130:131]
	s_add_i32 m0, s16, 0x2000
	s_nop 0
	global_load_lds_dwordx4 v[168:169], off
	v_lshl_add_u64 v[168:169], v[236:237], 0, s[84:85]
	s_mov_b32 m0, s29
	s_nop 0
	global_load_lds_dwordx4 v[168:169], off
	v_lshl_add_u64 v[168:169], v[238:239], 0, s[84:85]
	s_mov_b32 m0, s30
	s_nop 0
	global_load_lds_dwordx4 v[168:169], off
	s_waitcnt vmcnt(8)
	s_waitcnt lgkmcnt(0)
	s_barrier
	s_setprio 1
	s_waitcnt lgkmcnt(0)
	v_mfma_f32_16x16x32_bf16 v[62:65], v[164:167], v[204:207], v[62:65]
	v_mfma_f32_16x16x32_bf16 v[58:61], v[176:179], v[204:207], v[58:61]
	v_mfma_f32_16x16x32_bf16 v[54:57], v[164:167], v[212:215], v[54:57]
	v_mfma_f32_16x16x32_bf16 v[46:49], v[176:179], v[212:215], v[46:49]
	v_mfma_f32_16x16x32_bf16 v[38:41], v[164:167], v[220:223], v[38:41]
	v_mfma_f32_16x16x32_bf16 v[30:33], v[176:179], v[220:223], v[30:33]
	v_mfma_f32_16x16x32_bf16 v[22:25], v[164:167], v[228:231], v[22:25]
	v_mfma_f32_16x16x32_bf16 v[14:17], v[176:179], v[228:231], v[14:17]
	v_mfma_f32_16x16x32_bf16 v[62:65], v[172:175], v[208:211], v[62:65]
	v_mfma_f32_16x16x32_bf16 v[58:61], v[184:187], v[208:211], v[58:61]
	v_mfma_f32_16x16x32_bf16 v[54:57], v[172:175], v[216:219], v[54:57]
	v_mfma_f32_16x16x32_bf16 v[46:49], v[184:187], v[216:219], v[46:49]
	v_mfma_f32_16x16x32_bf16 v[38:41], v[172:175], v[224:227], v[38:41]
	v_mfma_f32_16x16x32_bf16 v[30:33], v[184:187], v[224:227], v[30:33]
	v_mfma_f32_16x16x32_bf16 v[22:25], v[172:175], v[232:235], v[22:25]
	v_mfma_f32_16x16x32_bf16 v[14:17], v[184:187], v[232:235], v[14:17]
	s_setprio 0
	s_setprio 1
	v_mfma_f32_16x16x32_bf16 v[50:53], v[188:191], v[204:207], v[50:53]
	v_mfma_f32_16x16x32_bf16 v[42:45], v[196:199], v[204:207], v[42:45]
	v_mfma_f32_16x16x32_bf16 v[34:37], v[188:191], v[212:215], v[34:37]
	v_mfma_f32_16x16x32_bf16 v[26:29], v[196:199], v[212:215], v[26:29]
	v_mfma_f32_16x16x32_bf16 v[18:21], v[188:191], v[220:223], v[18:21]
	v_mfma_f32_16x16x32_bf16 v[10:13], v[196:199], v[220:223], v[10:13]
	v_mfma_f32_16x16x32_bf16 v[6:9], v[188:191], v[228:231], v[6:9]
	v_mfma_f32_16x16x32_bf16 v[2:5], v[196:199], v[228:231], v[2:5]
	v_mfma_f32_16x16x32_bf16 v[50:53], v[192:195], v[208:211], v[50:53]
	v_mfma_f32_16x16x32_bf16 v[42:45], v[200:203], v[208:211], v[42:45]
	v_mfma_f32_16x16x32_bf16 v[34:37], v[192:195], v[216:219], v[34:37]
	v_mfma_f32_16x16x32_bf16 v[26:29], v[200:203], v[216:219], v[26:29]
	v_mfma_f32_16x16x32_bf16 v[18:21], v[192:195], v[224:227], v[18:21]
	v_mfma_f32_16x16x32_bf16 v[10:13], v[200:203], v[224:227], v[10:13]
	v_mfma_f32_16x16x32_bf16 v[6:9], v[192:195], v[232:235], v[6:9]
	v_mfma_f32_16x16x32_bf16 v[2:5], v[200:203], v[232:235], v[2:5]
	s_setprio 0
	s_barrier
	s_add_i32 s40, s40, 2
	s_add_u32 s38, s38, 0x100
	s_addc_u32 s39, s39, 0
	s_cmp_gt_u32 s40, 13
	s_mov_b64 s[16:17], s[18:19]
	s_cbranch_scc0 .LBB0_345
	s_mov_b32 s97, 0
	s_and_b64 vcc, exec, s[10:11]
	s_cbranch_vccnz .LBB0_350
	v_lshl_add_u32 v164, s37, 8, v1
	s_cmp_gt_i32 s36, 23
	s_mov_b64 s[4:5], -1
	s_cbranch_scc1 .LBB0_351

; #define PG8_STAGE(bufoff, gbase, voff) do { _Pragma("unroll") for (int _i = 0; _i < 2; ++_i) \
;         __builtin_amdgcn_global_load_lds((const unsigned*)((const char*)(gbase) + (voff)[_i]), (LAS unsigned*)(lds + (bufoff) + ldsw + _i * 8192), 16, 0, 0); } while (0)
; #define PG8_LDA(dst, b, h) do { _Pragma("unroll") for (int m = 0; m < 4; ++m) _Pragma("unroll") for (int k = 0; k < 2; ++k) dst[m][k] = *(const LAS bf16x8*)(lds + PG8_SA(b, h) + aoff + m * 2048 + k * 1024); } while (0)
; #define PG8_LDB(dst, b, h) do { _Pragma("unroll") for (int n = 0; n < 2; ++n) _Pragma("unroll") for (int k = 0; k < 2; ++k) dst[n][k] = *(const LAS bf16x8*)(lds + PG8_SB(b, h) + boff + n * 2048 + k * 1024); } while (0)
; #define PG8_MMA(ai, bj, At, Bt) do { __builtin_amdgcn_s_setprio(1); _Pragma("unroll") for (int m = 0; m < 4; ++m) _Pragma("unroll") for (int n = 0; n < 2; ++n) _Pragma("unroll") for (int k = 0; k < 2; ++k) \
;         acc[ai][bj][m][n] = __builtin_amdgcn_mfma_f32_16x16x32_bf16(Bt[n][k], At[m][k], acc[ai][bj][m][n], 0, 0, 0); __builtin_amdgcn_s_setprio(0); } while (0)
; #define PG8_WAIT_V(n) asm volatile("s_waitcnt vmcnt(" #n ")" ::: "memory")
; #define PG8_WAIT_L(n) asm volatile("s_waitcnt lgkmcnt(" #n ")" ::: "memory")
; #define PG8_BAR __builtin_amdgcn_s_barrier()
; #define PG8_SCHED __builtin_amdgcn_sched_barrier(0)
; template <class Epi, bool ALIGN_EPI = PG8_ALIGN, bool SP2 = PG8_SP2>
; __device__ __forceinline__ void gemm_phase(LAS uchar* lds, const Gemm g, const StaticOrder& S, const Epi& E) {
;     ...
;         for (int t = tb; t < tb + tblk; t += 2) {
;             const bool last = (t == nt - 2);
;             const char* a1 = cA + (size_t)(t + 1) * kstep;
;             const char* a2 = last ? nA : cA + (size_t)(t + 2) * kstep; const char* b2 = last ? nB : cB + (size_t)(t + 2) * kstep;
;             const char* a3 = a2 + kstep; const char* b3 = b2 + kstep;
;             if constexpr (SP2) {
;             PG8_LDB(B0, 0, 0); PG8_LDB(B1, 0, 1); PG8_SCHED; PG8_LDA(At, 0, 0); PG8_STAGE(PG8_SA(1, 1), a1 + hstepA, voffA);
;             PG8_WAIT_V(8); PG8_WAIT_L(0); PG8_BAR; PG8_MMA(0, 0, At, B0); PG8_MMA(0, 1, At, B1); PG8_BAR; PG8_SCHED;
.LBB0_1049:
	s_add_u32 s36, s14, 0x100
	s_addc_u32 s37, s15, 0
	s_mov_b32 s38, -2
	s_add_u32 s14, s12, 0x100
	s_addc_u32 s15, s13, 0
	s_add_i32 s39, 0, 0x10000
	s_cmp_eq_u32 s38, 12
	s_cselect_b32 s19, s1, s15
	s_cselect_b32 s18, s0, s14
	v_add_u32_e32 v144, s39, v139
	s_cselect_b32 s17, s11, s37
	s_cselect_b32 s16, s10, s36
	s_add_i32 s40, 0, 0x14000
	ds_read_b128 v[164:167], v144
	ds_read_b128 v[168:171], v144 offset:1024
	ds_read_b128 v[172:175], v144 offset:2048
	ds_read_b128 v[176:179], v144 offset:3072
	v_add_u32_e32 v144, s40, v139
	ds_read_b128 v[184:187], v144
	ds_read_b128 v[188:191], v144 offset:1024
	ds_read_b128 v[192:195], v144 offset:2048
	ds_read_b128 v[196:199], v144 offset:3072
	v_lshl_add_u64 v[160:161], s[12:13], 0, v[156:157]
	s_add_i32 m0, s23, 0xc000
	ds_read_b128 v[200:203], v163
	ds_read_b128 v[204:207], v163 offset:1024
	ds_read_b128 v[208:211], v163 offset:2048
	ds_read_b128 v[212:215], v163 offset:3072
	ds_read_b128 v[216:219], v163 offset:4096
	ds_read_b128 v[220:223], v163 offset:5120
	ds_read_b128 v[224:227], v163 offset:6144
	ds_read_b128 v[228:231], v163 offset:7168
	global_load_lds_dwordx4 v[160:161], off
	v_lshl_add_u64 v[160:161], s[12:13], 0, v[158:159]
	s_add_i32 m0, s23, 0xe000
	s_nop 0
	global_load_lds_dwordx4 v[160:161], off
	s_cmp_lt_u32 s29, 2
	s_cbranch_scc1 .Lrw_std_1050_0_pl
	s_waitcnt vmcnt(16)
	s_branch .Lrw_done_1050_0_pl

; #define PG8_STAGE(bufoff, gbase, voff) do { _Pragma("unroll") for (int _i = 0; _i < 2; ++_i) \
;         __builtin_amdgcn_global_load_lds((const unsigned*)((const char*)(gbase) + (voff)[_i]), (LAS unsigned*)(lds + (bufoff) + ldsw + _i * 8192), 16, 0, 0); } while (0)
; #define PG8_LDA(dst, b, h) do { _Pragma("unroll") for (int m = 0; m < 4; ++m) _Pragma("unroll") for (int k = 0; k < 2; ++k) dst[m][k] = *(const LAS bf16x8*)(lds + PG8_SA(b, h) + aoff + m * 2048 + k * 1024); } while (0)
; #define PG8_MMA(ai, bj, At, Bt) do { __builtin_amdgcn_s_setprio(1); _Pragma("unroll") for (int m = 0; m < 4; ++m) _Pragma("unroll") for (int n = 0; n < 2; ++n) _Pragma("unroll") for (int k = 0; k < 2; ++k) \
;         acc[ai][bj][m][n] = __builtin_amdgcn_mfma_f32_16x16x32_bf16(Bt[n][k], At[m][k], acc[ai][bj][m][n], 0, 0, 0); __builtin_amdgcn_s_setprio(0); } while (0)
; #define PG8_WAIT_V(n) asm volatile("s_waitcnt vmcnt(" #n ")" ::: "memory")
; #define PG8_WAIT_L(n) asm volatile("s_waitcnt lgkmcnt(" #n ")" ::: "memory")
; #define PG8_BAR __builtin_amdgcn_s_barrier()
; #define PG8_SCHED __builtin_amdgcn_sched_barrier(0)
; template <class Epi, bool ALIGN_EPI = PG8_ALIGN, bool SP2 = PG8_SP2>
; __device__ __forceinline__ void gemm_phase(LAS uchar* lds, const Gemm g, const StaticOrder& S, const Epi& E) {
;     ...
;             PG8_WAIT_V(8); PG8_WAIT_L(0); PG8_BAR; PG8_MMA(0, 0, At, B0); PG8_MMA(0, 1, At, B1); PG8_BAR; PG8_SCHED;
;             PG8_LDA(At, 0, 1); PG8_STAGE(PG8_SB(0, 0), b2, voffB); PG8_STAGE(PG8_SB(0, 1), b2 + hstepB, voffB); PG8_STAGE(PG8_SA(0, 0), a2, voffA);
;             PG8_WAIT_V(8); PG8_WAIT_L(0); PG8_BAR; PG8_MMA(1, 0, At, B0); PG8_MMA(1, 1, At, B1); PG8_BAR; PG8_SCHED;
.Lrw_done_1050_0_pl:
	s_waitcnt lgkmcnt(0)
	s_barrier
	s_setprio 1
	s_waitcnt lgkmcnt(0)
	v_mfma_f32_16x16x32_bf16 v[126:129], v[164:167], v[200:203], 0
	v_mfma_f32_16x16x32_bf16 v[118:121], v[172:175], v[200:203], 0
	v_mfma_f32_16x16x32_bf16 v[110:113], v[164:167], v[208:211], 0
	v_mfma_f32_16x16x32_bf16 v[102:105], v[172:175], v[208:211], 0
	v_mfma_f32_16x16x32_bf16 v[94:97], v[164:167], v[216:219], 0
	v_mfma_f32_16x16x32_bf16 v[86:89], v[172:175], v[216:219], 0
	v_mfma_f32_16x16x32_bf16 v[78:81], v[164:167], v[224:227], 0
	v_mfma_f32_16x16x32_bf16 v[70:73], v[172:175], v[224:227], 0
	v_mfma_f32_16x16x32_bf16 v[126:129], v[168:171], v[204:207], v[126:129]
	v_mfma_f32_16x16x32_bf16 v[118:121], v[176:179], v[204:207], v[118:121]
	v_mfma_f32_16x16x32_bf16 v[110:113], v[168:171], v[212:215], v[110:113]
	v_mfma_f32_16x16x32_bf16 v[102:105], v[176:179], v[212:215], v[102:105]
	v_mfma_f32_16x16x32_bf16 v[94:97], v[168:171], v[220:223], v[94:97]
	v_mfma_f32_16x16x32_bf16 v[86:89], v[176:179], v[220:223], v[86:89]
	v_mfma_f32_16x16x32_bf16 v[78:81], v[168:171], v[228:231], v[78:81]
	v_mfma_f32_16x16x32_bf16 v[70:73], v[176:179], v[228:231], v[70:73]
	s_setprio 0
	s_setprio 1
	v_mfma_f32_16x16x32_bf16 v[122:125], v[184:187], v[200:203], 0
	v_mfma_f32_16x16x32_bf16 v[114:117], v[192:195], v[200:203], 0
	v_mfma_f32_16x16x32_bf16 v[106:109], v[184:187], v[208:211], 0
	v_mfma_f32_16x16x32_bf16 v[98:101], v[192:195], v[208:211], 0
	v_mfma_f32_16x16x32_bf16 v[90:93], v[184:187], v[216:219], 0
	v_mfma_f32_16x16x32_bf16 v[82:85], v[192:195], v[216:219], 0
	v_mfma_f32_16x16x32_bf16 v[74:77], v[184:187], v[224:227], 0
	v_mfma_f32_16x16x32_bf16 v[66:69], v[192:195], v[224:227], 0
	v_mfma_f32_16x16x32_bf16 v[122:125], v[188:191], v[204:207], v[122:125]
	v_mfma_f32_16x16x32_bf16 v[114:117], v[196:199], v[204:207], v[114:117]
	v_mfma_f32_16x16x32_bf16 v[106:109], v[188:191], v[212:215], v[106:109]
	v_mfma_f32_16x16x32_bf16 v[98:101], v[196:199], v[212:215], v[98:101]
	v_mfma_f32_16x16x32_bf16 v[90:93], v[188:191], v[220:223], v[90:93]
	v_mfma_f32_16x16x32_bf16 v[82:85], v[196:199], v[220:223], v[82:85]
	v_mfma_f32_16x16x32_bf16 v[74:77], v[188:191], v[228:231], v[74:77]
	v_mfma_f32_16x16x32_bf16 v[66:69], v[196:199], v[228:231], v[66:69]
	s_setprio 0
	s_barrier
	s_add_i32 s12, s39, s21
	v_lshl_add_u64 v[160:161], s[16:17], 0, v[134:135]
	s_mov_b32 m0, s12
	ds_read_b128 v[200:203], v163 offset:16384
	ds_read_b128 v[204:207], v163 offset:17408
	ds_read_b128 v[208:211], v163 offset:18432
	ds_read_b128 v[212:215], v163 offset:19456
	ds_read_b128 v[216:219], v163 offset:20480
	ds_read_b128 v[220:223], v163 offset:21504
	ds_read_b128 v[224:227], v163 offset:22528
	ds_read_b128 v[228:231], v163 offset:23552
	global_load_lds_dwordx4 v[160:161], off
	s_add_i32 m0, s12, 0x2000
	s_add_u32 s12, s16, 0x44000
	v_lshl_add_u64 v[180:181], s[16:17], 0, v[130:131]
	s_addc_u32 s13, s17, 0
	s_add_i32 s39, s40, s21
	global_load_lds_dwordx4 v[180:181], off
	v_lshl_add_u64 v[232:233], s[12:13], 0, v[134:135]
	s_mov_b32 m0, s39
	v_lshl_add_u64 v[234:235], s[18:19], 0, v[132:133]
	global_load_lds_dwordx4 v[232:233], off
	v_lshl_add_u64 v[232:233], s[12:13], 0, v[130:131]
	s_add_i32 m0, s39, 0x2000
	s_nop 0
	global_load_lds_dwordx4 v[232:233], off
	v_lshl_add_u64 v[232:233], s[18:19], 0, v[154:155]
	s_mov_b32 m0, s23
	s_nop 0
	global_load_lds_dwordx4 v[232:233], off
	s_mov_b32 m0, s24
	s_nop 0
	global_load_lds_dwordx4 v[234:235], off
	s_cmp_lt_u32 s29, 2
	s_cbranch_scc1 .Lrw_std_1050_1_pl
	s_waitcnt vmcnt(16)
	s_branch .Lrw_done_1050_1_pl
